# v73 plus grid barrier one-level release: non-leader workgroups poll the cross-XCD release word directly instead of the per-XCD word their leader bumps afterwards (one dependent hop fewer per barrier)
# baseline (speedup 1.0000x reference)
; __device__ __forceinline__ unsigned xb_ld(unsigned* p)              { return __hip_atomic_load(p, __ATOMIC_RELAXED, __HIP_MEMORY_SCOPE_AGENT); }
; __device__ __forceinline__ unsigned xb_add(unsigned* p, unsigned v) { return __hip_atomic_fetch_add(p, v, __ATOMIC_RELAXED, __HIP_MEMORY_SCOPE_AGENT); }
; #define XB_SPIN(cond, bar) do { unsigned _sp = 0; while (cond) { __builtin_amdgcn_s_sleep(1); \
;     if ((++_sp & 255u) == 0u) { if (xb_ld(&(bar)[XB_TMO])) break; if (_sp > XB_SPIN_CAP) { atomicAdd(&(bar)[XB_TMO], 1u); break; } } } } while (0)
; __device__ __forceinline__ void xcd_barrier(const XcdBarrier& b) {
;     ...
;         const unsigned old = xb_add(&bar[XB_XSUB(b.x)], 1u);
;         const unsigned gen = old / nloc;
;         if (old + 1u == (gen + 1u) * nloc) {
;             __builtin_amdgcn_fence(__ATOMIC_RELEASE, "agent");
;             asm volatile("s_waitcnt vmcnt(0)" ::: "memory");
;             const unsigned og = xb_add(&bar[XB_TOP], 1u);
;             const unsigned tg = og / nx;
;             if (og + 1u == (tg + 1u) * nx) xb_add(&bar[XB_TOPGEN], 1u);
;             else XB_SPIN(xb_ld(&bar[XB_TOPGEN]) == tg, bar);
;             __builtin_amdgcn_fence(__ATOMIC_ACQUIRE, "agent");
;             xb_add(&bar[XB_XGEN(b.x)], 1u);
;             asm volatile("s_waitcnt vmcnt(0)" ::: "memory");
;         } else {
;             XB_SPIN(xb_ld(&bar[XB_XGEN(b.x)]) == gen, bar);
;             __builtin_amdgcn_fence(__ATOMIC_ACQUIRE, "agent");
;             asm volatile("s_waitcnt vmcnt(0)" ::: "memory");
;         }
.LBB0_174:
	s_or_b64 exec, exec, s[6:7]
	v_cvt_f32_u32_e32 v4, v2
	s_waitcnt vmcnt(0)
	v_readfirstlane_b32 s4, v3
	v_sub_u32_e32 v3, 0, v2
	v_rcp_iflag_f32_e32 v4, v4
	v_add_u32_e32 v5, s4, v1
	v_mul_f32_e32 v4, 0x4f7ffffe, v4
	v_cvt_u32_f32_e32 v4, v4
	v_mul_lo_u32 v1, v3, v4
	v_mul_hi_u32 v1, v4, v1
	v_add_u32_e32 v1, v4, v1
	v_mul_hi_u32 v1, v5, v1
	v_mul_lo_u32 v3, v1, v2
	v_sub_u32_e32 v3, v5, v3
	v_add_u32_e32 v4, 1, v1
	v_cmp_ge_u32_e32 vcc, v3, v2
	s_nop 1
	v_cndmask_b32_e32 v1, v1, v4, vcc
	v_sub_u32_e32 v4, v3, v2
	v_cndmask_b32_e32 v3, v3, v4, vcc
	v_add_u32_e32 v4, 1, v1
	v_cmp_ge_u32_e32 vcc, v3, v2
	v_add_u32_e32 v3, 1, v5
	s_nop 0
	v_cndmask_b32_e32 v1, v1, v4, vcc
	v_mul_lo_u32 v4, v2, v1
	v_add_u32_e32 v2, v4, v2
	v_cmp_ne_u32_e32 vcc, v3, v2
	s_and_saveexec_b64 s[4:5], vcc
	s_xor_b64 s[4:5], exec, s[4:5]
	s_cbranch_execz .LBB0_188
	s_waitcnt lgkmcnt(0)
	s_add_u32 s10, s94, 0x1f803500
	s_addc_u32 s11, s95, 0
	v_mov_b32_e32 v0, 0
	s_nop 0
	global_load_dword v0, v0, s[10:11] sc1
	s_waitcnt vmcnt(0)
	v_cmp_eq_u32_e32 vcc, v0, v1
	s_and_saveexec_b64 s[6:7], vcc
	s_cbranch_execz .LBB0_187
	s_add_u32 s8, s94, 0x1f800200
	s_addc_u32 s9, s95, 0
	s_mov_b32 s30, 1
	s_mov_b64 s[14:15], 0
	v_mov_b32_e32 v0, 0
	s_branch .LBB0_178

; __device__ __forceinline__ unsigned xb_ld(unsigned* p)              { return __hip_atomic_load(p, __ATOMIC_RELAXED, __HIP_MEMORY_SCOPE_AGENT); }
; __device__ __forceinline__ unsigned xb_add(unsigned* p, unsigned v) { return __hip_atomic_fetch_add(p, v, __ATOMIC_RELAXED, __HIP_MEMORY_SCOPE_AGENT); }
; #define XB_SPIN(cond, bar) do { unsigned _sp = 0; while (cond) { __builtin_amdgcn_s_sleep(1); \
;     if ((++_sp & 255u) == 0u) { if (xb_ld(&(bar)[XB_TMO])) break; if (_sp > XB_SPIN_CAP) { atomicAdd(&(bar)[XB_TMO], 1u); break; } } } } while (0)
; __device__ __forceinline__ void xcd_barrier(const XcdBarrier& b) {
;     ...
;         const unsigned old = xb_add(&bar[XB_XSUB(b.x)], 1u);
;         const unsigned gen = old / nloc;
;         if (old + 1u == (gen + 1u) * nloc) {
;             __builtin_amdgcn_fence(__ATOMIC_RELEASE, "agent");
;             asm volatile("s_waitcnt vmcnt(0)" ::: "memory");
;             const unsigned og = xb_add(&bar[XB_TOP], 1u);
;             const unsigned tg = og / nx;
;             if (og + 1u == (tg + 1u) * nx) xb_add(&bar[XB_TOPGEN], 1u);
;             else XB_SPIN(xb_ld(&bar[XB_TOPGEN]) == tg, bar);
;             __builtin_amdgcn_fence(__ATOMIC_ACQUIRE, "agent");
;             xb_add(&bar[XB_XGEN(b.x)], 1u);
;             asm volatile("s_waitcnt vmcnt(0)" ::: "memory");
;         } else {
;             XB_SPIN(xb_ld(&bar[XB_XGEN(b.x)]) == gen, bar);
;             __builtin_amdgcn_fence(__ATOMIC_ACQUIRE, "agent");
;             asm volatile("s_waitcnt vmcnt(0)" ::: "memory");
;         }
.LBB0_309:
	s_or_b64 exec, exec, s[6:7]
	v_cvt_f32_u32_e32 v4, v2
	s_waitcnt vmcnt(0)
	v_readfirstlane_b32 s4, v3
	v_sub_u32_e32 v3, 0, v2
	v_rcp_iflag_f32_e32 v4, v4
	v_add_u32_e32 v5, s4, v1
	v_mul_f32_e32 v4, 0x4f7ffffe, v4
	v_cvt_u32_f32_e32 v4, v4
	v_mul_lo_u32 v1, v3, v4
	v_mul_hi_u32 v1, v4, v1
	v_add_u32_e32 v1, v4, v1
	v_mul_hi_u32 v1, v5, v1
	v_mul_lo_u32 v3, v1, v2
	v_sub_u32_e32 v3, v5, v3
	v_add_u32_e32 v4, 1, v1
	v_cmp_ge_u32_e32 vcc, v3, v2
	s_nop 1
	v_cndmask_b32_e32 v1, v1, v4, vcc
	v_sub_u32_e32 v4, v3, v2
	v_cndmask_b32_e32 v3, v3, v4, vcc
	v_add_u32_e32 v4, 1, v1
	v_cmp_ge_u32_e32 vcc, v3, v2
	v_add_u32_e32 v3, 1, v5
	s_nop 0
	v_cndmask_b32_e32 v1, v1, v4, vcc
	v_mul_lo_u32 v4, v2, v1
	v_add_u32_e32 v2, v4, v2
	v_cmp_ne_u32_e32 vcc, v3, v2
	s_and_saveexec_b64 s[4:5], vcc
	s_xor_b64 s[4:5], exec, s[4:5]
	s_cbranch_execz .LBB0_323
	s_waitcnt lgkmcnt(0)
	s_add_u32 s10, s94, 0x1f803500
	s_addc_u32 s11, s95, 0
	v_mov_b32_e32 v0, 0
	s_nop 0
	global_load_dword v0, v0, s[10:11] sc1
	s_waitcnt vmcnt(0)
	v_cmp_eq_u32_e32 vcc, v0, v1
	s_and_saveexec_b64 s[6:7], vcc
	s_cbranch_execz .LBB0_322
	s_add_u32 s8, s94, 0x1f800200
	s_addc_u32 s9, s95, 0
	s_mov_b32 s28, 1
	s_mov_b64 s[12:13], 0
	v_mov_b32_e32 v0, 0
	s_branch .LBB0_313

; __device__ __forceinline__ unsigned xb_ld(unsigned* p)              { return __hip_atomic_load(p, __ATOMIC_RELAXED, __HIP_MEMORY_SCOPE_AGENT); }
; __device__ __forceinline__ unsigned xb_add(unsigned* p, unsigned v) { return __hip_atomic_fetch_add(p, v, __ATOMIC_RELAXED, __HIP_MEMORY_SCOPE_AGENT); }
; #define XB_SPIN(cond, bar) do { unsigned _sp = 0; while (cond) { __builtin_amdgcn_s_sleep(1); \
;     if ((++_sp & 255u) == 0u) { if (xb_ld(&(bar)[XB_TMO])) break; if (_sp > XB_SPIN_CAP) { atomicAdd(&(bar)[XB_TMO], 1u); break; } } } } while (0)
; __device__ __forceinline__ void xcd_barrier(const XcdBarrier& b) {
;     ...
;         const unsigned old = xb_add(&bar[XB_XSUB(b.x)], 1u);
;         const unsigned gen = old / nloc;
;         if (old + 1u == (gen + 1u) * nloc) {
;             __builtin_amdgcn_fence(__ATOMIC_RELEASE, "agent");
;             asm volatile("s_waitcnt vmcnt(0)" ::: "memory");
;             const unsigned og = xb_add(&bar[XB_TOP], 1u);
;             const unsigned tg = og / nx;
;             if (og + 1u == (tg + 1u) * nx) xb_add(&bar[XB_TOPGEN], 1u);
;             else XB_SPIN(xb_ld(&bar[XB_TOPGEN]) == tg, bar);
;             __builtin_amdgcn_fence(__ATOMIC_ACQUIRE, "agent");
;             xb_add(&bar[XB_XGEN(b.x)], 1u);
;             asm volatile("s_waitcnt vmcnt(0)" ::: "memory");
;         } else {
;             XB_SPIN(xb_ld(&bar[XB_XGEN(b.x)]) == gen, bar);
;             __builtin_amdgcn_fence(__ATOMIC_ACQUIRE, "agent");
;             asm volatile("s_waitcnt vmcnt(0)" ::: "memory");
;         }
.LBB0_427:
	s_or_b64 exec, exec, s[8:9]
	v_cvt_f32_u32_e32 v4, v2
	s_waitcnt vmcnt(0)
	v_readfirstlane_b32 s4, v3
	v_sub_u32_e32 v3, 0, v2
	v_rcp_iflag_f32_e32 v4, v4
	v_add_u32_e32 v5, s4, v1
	v_mul_f32_e32 v4, 0x4f7ffffe, v4
	v_cvt_u32_f32_e32 v4, v4
	v_mul_lo_u32 v1, v3, v4
	v_mul_hi_u32 v1, v4, v1
	v_add_u32_e32 v1, v4, v1
	v_mul_hi_u32 v1, v5, v1
	v_mul_lo_u32 v3, v1, v2
	v_sub_u32_e32 v3, v5, v3
	v_add_u32_e32 v4, 1, v1
	v_cmp_ge_u32_e32 vcc, v3, v2
	s_nop 1
	v_cndmask_b32_e32 v1, v1, v4, vcc
	v_sub_u32_e32 v4, v3, v2
	v_cndmask_b32_e32 v3, v3, v4, vcc
	v_add_u32_e32 v4, 1, v1
	v_cmp_ge_u32_e32 vcc, v3, v2
	v_add_u32_e32 v3, 1, v5
	s_nop 0
	v_cndmask_b32_e32 v1, v1, v4, vcc
	v_mul_lo_u32 v4, v2, v1
	v_add_u32_e32 v2, v4, v2
	v_cmp_ne_u32_e32 vcc, v3, v2
	s_and_saveexec_b64 s[4:5], vcc
	s_xor_b64 s[4:5], exec, s[4:5]
	s_cbranch_execz .LBB0_441
	s_waitcnt lgkmcnt(0)
	s_add_u32 s14, s94, 0x1f803500
	s_addc_u32 s15, s95, 0
	v_mov_b32_e32 v0, 0
	s_nop 0
	global_load_dword v0, v0, s[14:15] sc1
	s_waitcnt vmcnt(0)
	v_cmp_eq_u32_e32 vcc, v0, v1
	s_and_saveexec_b64 s[8:9], vcc
	s_cbranch_execz .LBB0_440
	s_add_u32 s10, s94, 0x1f800200
	s_addc_u32 s11, s95, 0
	s_mov_b32 s6, 1
	s_mov_b64 s[16:17], 0
	v_mov_b32_e32 v0, 0
	s_branch .LBB0_431

; __device__ __forceinline__ unsigned xb_ld(unsigned* p)              { return __hip_atomic_load(p, __ATOMIC_RELAXED, __HIP_MEMORY_SCOPE_AGENT); }
; __device__ __forceinline__ unsigned xb_add(unsigned* p, unsigned v) { return __hip_atomic_fetch_add(p, v, __ATOMIC_RELAXED, __HIP_MEMORY_SCOPE_AGENT); }
; #define XB_SPIN(cond, bar) do { unsigned _sp = 0; while (cond) { __builtin_amdgcn_s_sleep(1); \
;     if ((++_sp & 255u) == 0u) { if (xb_ld(&(bar)[XB_TMO])) break; if (_sp > XB_SPIN_CAP) { atomicAdd(&(bar)[XB_TMO], 1u); break; } } } } while (0)
; __device__ __forceinline__ void xcd_barrier(const XcdBarrier& b) {
;     ...
;         const unsigned old = xb_add(&bar[XB_XSUB(b.x)], 1u);
;         const unsigned gen = old / nloc;
;         if (old + 1u == (gen + 1u) * nloc) {
;             __builtin_amdgcn_fence(__ATOMIC_RELEASE, "agent");
;             asm volatile("s_waitcnt vmcnt(0)" ::: "memory");
;             const unsigned og = xb_add(&bar[XB_TOP], 1u);
;             const unsigned tg = og / nx;
;             if (og + 1u == (tg + 1u) * nx) xb_add(&bar[XB_TOPGEN], 1u);
;             else XB_SPIN(xb_ld(&bar[XB_TOPGEN]) == tg, bar);
;             __builtin_amdgcn_fence(__ATOMIC_ACQUIRE, "agent");
;             xb_add(&bar[XB_XGEN(b.x)], 1u);
;             asm volatile("s_waitcnt vmcnt(0)" ::: "memory");
;         } else {
;             XB_SPIN(xb_ld(&bar[XB_XGEN(b.x)]) == gen, bar);
;             __builtin_amdgcn_fence(__ATOMIC_ACQUIRE, "agent");
;             asm volatile("s_waitcnt vmcnt(0)" ::: "memory");
;         }
.LBB0_560:
	s_or_b64 exec, exec, s[8:9]
	v_cvt_f32_u32_e32 v4, v2
	s_waitcnt vmcnt(0)
	v_readfirstlane_b32 s4, v3
	v_sub_u32_e32 v3, 0, v2
	v_rcp_iflag_f32_e32 v4, v4
	v_add_u32_e32 v5, s4, v1
	v_mul_f32_e32 v4, 0x4f7ffffe, v4
	v_cvt_u32_f32_e32 v4, v4
	v_mul_lo_u32 v1, v3, v4
	v_mul_hi_u32 v1, v4, v1
	v_add_u32_e32 v1, v4, v1
	v_mul_hi_u32 v1, v5, v1
	v_mul_lo_u32 v3, v1, v2
	v_sub_u32_e32 v3, v5, v3
	v_add_u32_e32 v4, 1, v1
	v_cmp_ge_u32_e32 vcc, v3, v2
	s_nop 1
	v_cndmask_b32_e32 v1, v1, v4, vcc
	v_sub_u32_e32 v4, v3, v2
	v_cndmask_b32_e32 v3, v3, v4, vcc
	v_add_u32_e32 v4, 1, v1
	v_cmp_ge_u32_e32 vcc, v3, v2
	v_add_u32_e32 v3, 1, v5
	s_nop 0
	v_cndmask_b32_e32 v1, v1, v4, vcc
	v_mul_lo_u32 v4, v2, v1
	v_add_u32_e32 v2, v4, v2
	v_cmp_ne_u32_e32 vcc, v3, v2
	s_and_saveexec_b64 s[4:5], vcc
	s_xor_b64 s[4:5], exec, s[4:5]
	s_cbranch_execz .LBB0_574
	s_waitcnt lgkmcnt(0)
	s_add_u32 s12, s94, 0x1f803500
	s_addc_u32 s13, s95, 0
	v_mov_b32_e32 v0, 0
	s_nop 0
	global_load_dword v0, v0, s[12:13] sc1
	s_waitcnt vmcnt(0)
	v_cmp_eq_u32_e32 vcc, v0, v1
	s_and_saveexec_b64 s[8:9], vcc
	s_cbranch_execz .LBB0_573
	s_add_u32 s10, s94, 0x1f800200
	s_addc_u32 s11, s95, 0
	s_mov_b32 s6, 1
	s_mov_b64 s[14:15], 0
	v_mov_b32_e32 v0, 0
	s_branch .LBB0_564

; __device__ __forceinline__ unsigned xb_ld(unsigned* p)              { return __hip_atomic_load(p, __ATOMIC_RELAXED, __HIP_MEMORY_SCOPE_AGENT); }
; __device__ __forceinline__ unsigned xb_add(unsigned* p, unsigned v) { return __hip_atomic_fetch_add(p, v, __ATOMIC_RELAXED, __HIP_MEMORY_SCOPE_AGENT); }
; #define XB_SPIN(cond, bar) do { unsigned _sp = 0; while (cond) { __builtin_amdgcn_s_sleep(1); \
;     if ((++_sp & 255u) == 0u) { if (xb_ld(&(bar)[XB_TMO])) break; if (_sp > XB_SPIN_CAP) { atomicAdd(&(bar)[XB_TMO], 1u); break; } } } } while (0)
; __device__ __forceinline__ void xcd_barrier(const XcdBarrier& b) {
;     ...
;         const unsigned old = xb_add(&bar[XB_XSUB(b.x)], 1u);
;         const unsigned gen = old / nloc;
;         if (old + 1u == (gen + 1u) * nloc) {
;             __builtin_amdgcn_fence(__ATOMIC_RELEASE, "agent");
;             asm volatile("s_waitcnt vmcnt(0)" ::: "memory");
;             const unsigned og = xb_add(&bar[XB_TOP], 1u);
;             const unsigned tg = og / nx;
;             if (og + 1u == (tg + 1u) * nx) xb_add(&bar[XB_TOPGEN], 1u);
;             else XB_SPIN(xb_ld(&bar[XB_TOPGEN]) == tg, bar);
;             __builtin_amdgcn_fence(__ATOMIC_ACQUIRE, "agent");
;             xb_add(&bar[XB_XGEN(b.x)], 1u);
;             asm volatile("s_waitcnt vmcnt(0)" ::: "memory");
;         } else {
;             XB_SPIN(xb_ld(&bar[XB_XGEN(b.x)]) == gen, bar);
;             __builtin_amdgcn_fence(__ATOMIC_ACQUIRE, "agent");
;             asm volatile("s_waitcnt vmcnt(0)" ::: "memory");
;         }
.LBB0_769:
	s_or_b64 exec, exec, s[10:11]
	v_cvt_f32_u32_e32 v4, v2
	s_waitcnt vmcnt(0)
	v_readfirstlane_b32 s4, v3
	v_sub_u32_e32 v3, 0, v2
	v_rcp_iflag_f32_e32 v4, v4
	v_add_u32_e32 v5, s4, v1
	v_mul_f32_e32 v4, 0x4f7ffffe, v4
	v_cvt_u32_f32_e32 v4, v4
	v_mul_lo_u32 v1, v3, v4
	v_mul_hi_u32 v1, v4, v1
	v_add_u32_e32 v1, v4, v1
	v_mul_hi_u32 v1, v5, v1
	v_mul_lo_u32 v3, v1, v2
	v_sub_u32_e32 v3, v5, v3
	v_add_u32_e32 v4, 1, v1
	v_cmp_ge_u32_e32 vcc, v3, v2
	s_nop 1
	v_cndmask_b32_e32 v1, v1, v4, vcc
	v_sub_u32_e32 v4, v3, v2
	v_cndmask_b32_e32 v3, v3, v4, vcc
	v_add_u32_e32 v4, 1, v1
	v_cmp_ge_u32_e32 vcc, v3, v2
	v_add_u32_e32 v3, 1, v5
	s_nop 0
	v_cndmask_b32_e32 v1, v1, v4, vcc
	v_mul_lo_u32 v4, v2, v1
	v_add_u32_e32 v2, v4, v2
	v_cmp_ne_u32_e32 vcc, v3, v2
	s_and_saveexec_b64 s[4:5], vcc
	s_xor_b64 s[8:9], exec, s[4:5]
	s_cbranch_execz .LBB0_783
	s_waitcnt lgkmcnt(0)
	s_add_u32 s16, s94, 0x1f803500
	s_addc_u32 s17, s95, 0
	v_mov_b32_e32 v0, 0
	s_nop 0
	global_load_dword v0, v0, s[16:17] sc1
	s_waitcnt vmcnt(0)
	v_cmp_eq_u32_e32 vcc, v0, v1
	s_and_saveexec_b64 s[10:11], vcc
	s_cbranch_execz .LBB0_782
	s_add_u32 s14, s94, 0x1f800200
	s_addc_u32 s15, s95, 0
	s_mov_b32 s4, 1
	s_mov_b64 s[18:19], 0
	v_mov_b32_e32 v0, 0
	s_branch .LBB0_773

; __device__ __forceinline__ unsigned xb_ld(unsigned* p)              { return __hip_atomic_load(p, __ATOMIC_RELAXED, __HIP_MEMORY_SCOPE_AGENT); }
; __device__ __forceinline__ unsigned xb_add(unsigned* p, unsigned v) { return __hip_atomic_fetch_add(p, v, __ATOMIC_RELAXED, __HIP_MEMORY_SCOPE_AGENT); }
; #define XB_SPIN(cond, bar) do { unsigned _sp = 0; while (cond) { __builtin_amdgcn_s_sleep(1); \
;     if ((++_sp & 255u) == 0u) { if (xb_ld(&(bar)[XB_TMO])) break; if (_sp > XB_SPIN_CAP) { atomicAdd(&(bar)[XB_TMO], 1u); break; } } } } while (0)
; __device__ __forceinline__ void xcd_barrier(const XcdBarrier& b) {
;     ...
;         const unsigned old = xb_add(&bar[XB_XSUB(b.x)], 1u);
;         const unsigned gen = old / nloc;
;         if (old + 1u == (gen + 1u) * nloc) {
;             __builtin_amdgcn_fence(__ATOMIC_RELEASE, "agent");
;             asm volatile("s_waitcnt vmcnt(0)" ::: "memory");
;             const unsigned og = xb_add(&bar[XB_TOP], 1u);
;             const unsigned tg = og / nx;
;             if (og + 1u == (tg + 1u) * nx) xb_add(&bar[XB_TOPGEN], 1u);
;             else XB_SPIN(xb_ld(&bar[XB_TOPGEN]) == tg, bar);
;             __builtin_amdgcn_fence(__ATOMIC_ACQUIRE, "agent");
;             xb_add(&bar[XB_XGEN(b.x)], 1u);
;             asm volatile("s_waitcnt vmcnt(0)" ::: "memory");
;         } else {
;             XB_SPIN(xb_ld(&bar[XB_XGEN(b.x)]) == gen, bar);
;             __builtin_amdgcn_fence(__ATOMIC_ACQUIRE, "agent");
;             asm volatile("s_waitcnt vmcnt(0)" ::: "memory");
;         }
.LBB0_1043:
	s_or_b64 exec, exec, s[10:11]
	v_cvt_f32_u32_e32 v4, v2
	s_waitcnt vmcnt(0)
	v_readfirstlane_b32 s4, v3
	v_sub_u32_e32 v3, 0, v2
	v_rcp_iflag_f32_e32 v4, v4
	v_add_u32_e32 v5, s4, v1
	v_mul_f32_e32 v4, 0x4f7ffffe, v4
	v_cvt_u32_f32_e32 v4, v4
	v_mul_lo_u32 v1, v3, v4
	v_mul_hi_u32 v1, v4, v1
	v_add_u32_e32 v1, v4, v1
	v_mul_hi_u32 v1, v5, v1
	v_mul_lo_u32 v3, v1, v2
	v_sub_u32_e32 v3, v5, v3
	v_add_u32_e32 v4, 1, v1
	v_cmp_ge_u32_e32 vcc, v3, v2
	s_nop 1
	v_cndmask_b32_e32 v1, v1, v4, vcc
	v_sub_u32_e32 v4, v3, v2
	v_cndmask_b32_e32 v3, v3, v4, vcc
	v_add_u32_e32 v4, 1, v1
	v_cmp_ge_u32_e32 vcc, v3, v2
	v_add_u32_e32 v3, 1, v5
	s_nop 0
	v_cndmask_b32_e32 v1, v1, v4, vcc
	v_mul_lo_u32 v4, v2, v1
	v_add_u32_e32 v2, v4, v2
	v_cmp_ne_u32_e32 vcc, v3, v2
	s_and_saveexec_b64 s[4:5], vcc
	s_xor_b64 s[8:9], exec, s[4:5]
	s_cbranch_execz .LBB0_1057
	s_waitcnt lgkmcnt(0)
	s_add_u32 s14, s94, 0x1f803500
	s_addc_u32 s15, s95, 0
	v_mov_b32_e32 v0, 0
	s_nop 0
	global_load_dword v0, v0, s[14:15] sc1
	s_waitcnt vmcnt(0)
	v_cmp_eq_u32_e32 vcc, v0, v1
	s_and_saveexec_b64 s[10:11], vcc
	s_cbranch_execz .LBB0_1056
	s_add_u32 s12, s94, 0x1f800200
	s_addc_u32 s13, s95, 0
	s_mov_b32 s4, 1
	s_mov_b64 s[16:17], 0
	v_mov_b32_e32 v0, 0
	s_branch .LBB0_1047

; __device__ __forceinline__ unsigned xb_ld(unsigned* p)              { return __hip_atomic_load(p, __ATOMIC_RELAXED, __HIP_MEMORY_SCOPE_AGENT); }
; __device__ __forceinline__ unsigned xb_add(unsigned* p, unsigned v) { return __hip_atomic_fetch_add(p, v, __ATOMIC_RELAXED, __HIP_MEMORY_SCOPE_AGENT); }
; #define XB_SPIN(cond, bar) do { unsigned _sp = 0; while (cond) { __builtin_amdgcn_s_sleep(1); \
;     if ((++_sp & 255u) == 0u) { if (xb_ld(&(bar)[XB_TMO])) break; if (_sp > XB_SPIN_CAP) { atomicAdd(&(bar)[XB_TMO], 1u); break; } } } } while (0)
; __device__ __forceinline__ void xcd_barrier(const XcdBarrier& b) {
;     ...
;         const unsigned old = xb_add(&bar[XB_XSUB(b.x)], 1u);
;         const unsigned gen = old / nloc;
;         if (old + 1u == (gen + 1u) * nloc) {
;             __builtin_amdgcn_fence(__ATOMIC_RELEASE, "agent");
;             asm volatile("s_waitcnt vmcnt(0)" ::: "memory");
;             const unsigned og = xb_add(&bar[XB_TOP], 1u);
;             const unsigned tg = og / nx;
;             if (og + 1u == (tg + 1u) * nx) xb_add(&bar[XB_TOPGEN], 1u);
;             else XB_SPIN(xb_ld(&bar[XB_TOPGEN]) == tg, bar);
;             __builtin_amdgcn_fence(__ATOMIC_ACQUIRE, "agent");
;             xb_add(&bar[XB_XGEN(b.x)], 1u);
;             asm volatile("s_waitcnt vmcnt(0)" ::: "memory");
;         } else {
;             XB_SPIN(xb_ld(&bar[XB_XGEN(b.x)]) == gen, bar);
;             __builtin_amdgcn_fence(__ATOMIC_ACQUIRE, "agent");
;             asm volatile("s_waitcnt vmcnt(0)" ::: "memory");
;         }
.LBB0_1165:
	s_or_b64 exec, exec, s[12:13]
	v_cvt_f32_u32_e32 v4, v2
	s_waitcnt vmcnt(0)
	v_readfirstlane_b32 s4, v3
	v_sub_u32_e32 v3, 0, v2
	v_rcp_iflag_f32_e32 v4, v4
	v_add_u32_e32 v5, s4, v1
	v_mul_f32_e32 v4, 0x4f7ffffe, v4
	v_cvt_u32_f32_e32 v4, v4
	v_mul_lo_u32 v1, v3, v4
	v_mul_hi_u32 v1, v4, v1
	v_add_u32_e32 v1, v4, v1
	v_mul_hi_u32 v1, v5, v1
	v_mul_lo_u32 v3, v1, v2
	v_sub_u32_e32 v3, v5, v3
	v_add_u32_e32 v4, 1, v1
	v_cmp_ge_u32_e32 vcc, v3, v2
	s_nop 1
	v_cndmask_b32_e32 v1, v1, v4, vcc
	v_sub_u32_e32 v4, v3, v2
	v_cndmask_b32_e32 v3, v3, v4, vcc
	v_add_u32_e32 v4, 1, v1
	v_cmp_ge_u32_e32 vcc, v3, v2
	v_add_u32_e32 v3, 1, v5
	s_nop 0
	v_cndmask_b32_e32 v1, v1, v4, vcc
	v_mul_lo_u32 v4, v2, v1
	v_add_u32_e32 v2, v4, v2
	v_cmp_ne_u32_e32 vcc, v3, v2
	s_and_saveexec_b64 s[4:5], vcc
	s_xor_b64 s[8:9], exec, s[4:5]
	s_cbranch_execz .LBB0_1179
	s_waitcnt lgkmcnt(0)
	s_add_u32 s16, s94, 0x1f803500
	s_addc_u32 s17, s95, 0
	v_mov_b32_e32 v0, 0
	s_nop 0
	global_load_dword v0, v0, s[16:17] sc1
	s_waitcnt vmcnt(0)
	v_cmp_eq_u32_e32 vcc, v0, v1
	s_and_saveexec_b64 s[12:13], vcc
	s_cbranch_execz .LBB0_1178
	s_add_u32 s14, s94, 0x1f800200
	s_addc_u32 s15, s95, 0
	s_mov_b32 s4, 1
	s_mov_b64 s[18:19], 0
	v_mov_b32_e32 v0, 0
	s_branch .LBB0_1169

; __device__ __forceinline__ unsigned xb_ld(unsigned* p)              { return __hip_atomic_load(p, __ATOMIC_RELAXED, __HIP_MEMORY_SCOPE_AGENT); }
; __device__ __forceinline__ unsigned xb_add(unsigned* p, unsigned v) { return __hip_atomic_fetch_add(p, v, __ATOMIC_RELAXED, __HIP_MEMORY_SCOPE_AGENT); }
; #define XB_SPIN(cond, bar) do { unsigned _sp = 0; while (cond) { __builtin_amdgcn_s_sleep(1); \
;     if ((++_sp & 255u) == 0u) { if (xb_ld(&(bar)[XB_TMO])) break; if (_sp > XB_SPIN_CAP) { atomicAdd(&(bar)[XB_TMO], 1u); break; } } } } while (0)
; __device__ __forceinline__ void xcd_barrier(const XcdBarrier& b) {
;     ...
;         const unsigned old = xb_add(&bar[XB_XSUB(b.x)], 1u);
;         const unsigned gen = old / nloc;
;         if (old + 1u == (gen + 1u) * nloc) {
;             __builtin_amdgcn_fence(__ATOMIC_RELEASE, "agent");
;             asm volatile("s_waitcnt vmcnt(0)" ::: "memory");
;             const unsigned og = xb_add(&bar[XB_TOP], 1u);
;             const unsigned tg = og / nx;
;             if (og + 1u == (tg + 1u) * nx) xb_add(&bar[XB_TOPGEN], 1u);
;             else XB_SPIN(xb_ld(&bar[XB_TOPGEN]) == tg, bar);
;             __builtin_amdgcn_fence(__ATOMIC_ACQUIRE, "agent");
;             xb_add(&bar[XB_XGEN(b.x)], 1u);
;             asm volatile("s_waitcnt vmcnt(0)" ::: "memory");
;         } else {
;             XB_SPIN(xb_ld(&bar[XB_XGEN(b.x)]) == gen, bar);
;             __builtin_amdgcn_fence(__ATOMIC_ACQUIRE, "agent");
;             asm volatile("s_waitcnt vmcnt(0)" ::: "memory");
;         }
.LBB0_2557:
	s_or_b64 exec, exec, s[8:9]
	v_cvt_f32_u32_e32 v4, v2
	s_waitcnt vmcnt(0)
	v_readfirstlane_b32 s4, v3
	v_sub_u32_e32 v3, 0, v2
	v_rcp_iflag_f32_e32 v4, v4
	v_add_u32_e32 v5, s4, v1
	v_mul_f32_e32 v4, 0x4f7ffffe, v4
	v_cvt_u32_f32_e32 v4, v4
	v_mul_lo_u32 v1, v3, v4
	v_mul_hi_u32 v1, v4, v1
	v_add_u32_e32 v1, v4, v1
	v_mul_hi_u32 v1, v5, v1
	v_mul_lo_u32 v3, v1, v2
	v_sub_u32_e32 v3, v5, v3
	v_add_u32_e32 v4, 1, v1
	v_cmp_ge_u32_e32 vcc, v3, v2
	s_nop 1
	v_cndmask_b32_e32 v1, v1, v4, vcc
	v_sub_u32_e32 v4, v3, v2
	v_cndmask_b32_e32 v3, v3, v4, vcc
	v_add_u32_e32 v4, 1, v1
	v_cmp_ge_u32_e32 vcc, v3, v2
	v_add_u32_e32 v3, 1, v5
	s_nop 0
	v_cndmask_b32_e32 v1, v1, v4, vcc
	v_mul_lo_u32 v4, v2, v1
	v_add_u32_e32 v2, v4, v2
	v_cmp_ne_u32_e32 vcc, v3, v2
	s_and_saveexec_b64 s[4:5], vcc
	s_xor_b64 s[6:7], exec, s[4:5]
	s_cbranch_execz .LBB0_2571
	s_waitcnt lgkmcnt(0)
	s_add_u32 s14, s94, 0x1f803500
	s_addc_u32 s15, s95, 0
	v_mov_b32_e32 v0, 0
	s_nop 0
	global_load_dword v0, v0, s[14:15] sc1
	s_waitcnt vmcnt(0)
	v_cmp_eq_u32_e32 vcc, v0, v1
	s_and_saveexec_b64 s[8:9], vcc
	s_cbranch_execz .LBB0_2570
	s_add_u32 s10, s94, 0x1f800200
	s_addc_u32 s11, s95, 0
	s_mov_b32 s4, 1
	s_mov_b64 s[16:17], 0
	v_mov_b32_e32 v0, 0
	s_branch .LBB0_2561

; __device__ __forceinline__ unsigned xb_ld(unsigned* p)              { return __hip_atomic_load(p, __ATOMIC_RELAXED, __HIP_MEMORY_SCOPE_AGENT); }
; __device__ __forceinline__ unsigned xb_add(unsigned* p, unsigned v) { return __hip_atomic_fetch_add(p, v, __ATOMIC_RELAXED, __HIP_MEMORY_SCOPE_AGENT); }
; #define XB_SPIN(cond, bar) do { unsigned _sp = 0; while (cond) { __builtin_amdgcn_s_sleep(1); \
;     if ((++_sp & 255u) == 0u) { if (xb_ld(&(bar)[XB_TMO])) break; if (_sp > XB_SPIN_CAP) { atomicAdd(&(bar)[XB_TMO], 1u); break; } } } } while (0)
; __device__ __forceinline__ void xcd_barrier(const XcdBarrier& b) {
;     ...
;         const unsigned old = xb_add(&bar[XB_XSUB(b.x)], 1u);
;         const unsigned gen = old / nloc;
;         if (old + 1u == (gen + 1u) * nloc) {
;             __builtin_amdgcn_fence(__ATOMIC_RELEASE, "agent");
;             asm volatile("s_waitcnt vmcnt(0)" ::: "memory");
;             const unsigned og = xb_add(&bar[XB_TOP], 1u);
;             const unsigned tg = og / nx;
;             if (og + 1u == (tg + 1u) * nx) xb_add(&bar[XB_TOPGEN], 1u);
;             else XB_SPIN(xb_ld(&bar[XB_TOPGEN]) == tg, bar);
;             __builtin_amdgcn_fence(__ATOMIC_ACQUIRE, "agent");
;             xb_add(&bar[XB_XGEN(b.x)], 1u);
;             asm volatile("s_waitcnt vmcnt(0)" ::: "memory");
;         } else {
;             XB_SPIN(xb_ld(&bar[XB_XGEN(b.x)]) == gen, bar);
;             __builtin_amdgcn_fence(__ATOMIC_ACQUIRE, "agent");
;             asm volatile("s_waitcnt vmcnt(0)" ::: "memory");
;         }
.LBB0_2691:
	s_or_b64 exec, exec, s[8:9]
	v_cvt_f32_u32_e32 v4, v2
	s_waitcnt vmcnt(0)
	v_readfirstlane_b32 s4, v3
	v_sub_u32_e32 v3, 0, v2
	v_rcp_iflag_f32_e32 v4, v4
	v_add_u32_e32 v5, s4, v1
	v_mul_f32_e32 v4, 0x4f7ffffe, v4
	v_cvt_u32_f32_e32 v4, v4
	v_mul_lo_u32 v1, v3, v4
	v_mul_hi_u32 v1, v4, v1
	v_add_u32_e32 v1, v4, v1
	v_mul_hi_u32 v1, v5, v1
	v_mul_lo_u32 v3, v1, v2
	v_sub_u32_e32 v3, v5, v3
	v_add_u32_e32 v4, 1, v1
	v_cmp_ge_u32_e32 vcc, v3, v2
	s_nop 1
	v_cndmask_b32_e32 v1, v1, v4, vcc
	v_sub_u32_e32 v4, v3, v2
	v_cndmask_b32_e32 v3, v3, v4, vcc
	v_add_u32_e32 v4, 1, v1
	v_cmp_ge_u32_e32 vcc, v3, v2
	v_add_u32_e32 v3, 1, v5
	s_nop 0
	v_cndmask_b32_e32 v1, v1, v4, vcc
	v_mul_lo_u32 v4, v2, v1
	v_add_u32_e32 v2, v4, v2
	v_cmp_ne_u32_e32 vcc, v3, v2
	s_and_saveexec_b64 s[4:5], vcc
	s_xor_b64 s[6:7], exec, s[4:5]
	s_cbranch_execz .LBB0_2705
	s_waitcnt lgkmcnt(0)
	s_add_u32 s12, s94, 0x1f803500
	s_addc_u32 s13, s95, 0
	v_mov_b32_e32 v0, 0
	s_nop 0
	global_load_dword v0, v0, s[12:13] sc1
	s_waitcnt vmcnt(0)
	v_cmp_eq_u32_e32 vcc, v0, v1
	s_and_saveexec_b64 s[8:9], vcc
	s_cbranch_execz .LBB0_2704
	s_add_u32 s10, s94, 0x1f800200
	s_addc_u32 s11, s95, 0
	s_mov_b32 s4, 1
	s_mov_b64 s[14:15], 0
	v_mov_b32_e32 v0, 0
	s_branch .LBB0_2695

; __device__ __forceinline__ unsigned xb_ld(unsigned* p)              { return __hip_atomic_load(p, __ATOMIC_RELAXED, __HIP_MEMORY_SCOPE_AGENT); }
; __device__ __forceinline__ unsigned xb_add(unsigned* p, unsigned v) { return __hip_atomic_fetch_add(p, v, __ATOMIC_RELAXED, __HIP_MEMORY_SCOPE_AGENT); }
; #define XB_SPIN(cond, bar) do { unsigned _sp = 0; while (cond) { __builtin_amdgcn_s_sleep(1); \
;     if ((++_sp & 255u) == 0u) { if (xb_ld(&(bar)[XB_TMO])) break; if (_sp > XB_SPIN_CAP) { atomicAdd(&(bar)[XB_TMO], 1u); break; } } } } while (0)
; __device__ __forceinline__ void xcd_barrier(const XcdBarrier& b) {
;     ...
;         const unsigned old = xb_add(&bar[XB_XSUB(b.x)], 1u);
;         const unsigned gen = old / nloc;
;         if (old + 1u == (gen + 1u) * nloc) {
;             __builtin_amdgcn_fence(__ATOMIC_RELEASE, "agent");
;             asm volatile("s_waitcnt vmcnt(0)" ::: "memory");
;             const unsigned og = xb_add(&bar[XB_TOP], 1u);
;             const unsigned tg = og / nx;
;             if (og + 1u == (tg + 1u) * nx) xb_add(&bar[XB_TOPGEN], 1u);
;             else XB_SPIN(xb_ld(&bar[XB_TOPGEN]) == tg, bar);
;             __builtin_amdgcn_fence(__ATOMIC_ACQUIRE, "agent");
;             xb_add(&bar[XB_XGEN(b.x)], 1u);
;             asm volatile("s_waitcnt vmcnt(0)" ::: "memory");
;         } else {
;             XB_SPIN(xb_ld(&bar[XB_XGEN(b.x)]) == gen, bar);
;             __builtin_amdgcn_fence(__ATOMIC_ACQUIRE, "agent");
;             asm volatile("s_waitcnt vmcnt(0)" ::: "memory");
;         }
.LBB0_2900:
	s_or_b64 exec, exec, s[6:7]
	v_cvt_f32_u32_e32 v4, v2
	s_waitcnt vmcnt(0)
	v_readfirstlane_b32 s4, v3
	v_sub_u32_e32 v3, 0, v2
	v_rcp_iflag_f32_e32 v4, v4
	v_add_u32_e32 v5, s4, v1
	v_mul_f32_e32 v4, 0x4f7ffffe, v4
	v_cvt_u32_f32_e32 v4, v4
	v_mul_lo_u32 v1, v3, v4
	v_mul_hi_u32 v1, v4, v1
	v_add_u32_e32 v1, v4, v1
	v_mul_hi_u32 v1, v5, v1
	v_mul_lo_u32 v3, v1, v2
	v_sub_u32_e32 v3, v5, v3
	v_add_u32_e32 v4, 1, v1
	v_cmp_ge_u32_e32 vcc, v3, v2
	s_nop 1
	v_cndmask_b32_e32 v1, v1, v4, vcc
	v_sub_u32_e32 v4, v3, v2
	v_cndmask_b32_e32 v3, v3, v4, vcc
	v_add_u32_e32 v4, 1, v1
	v_cmp_ge_u32_e32 vcc, v3, v2
	v_add_u32_e32 v3, 1, v5
	s_nop 0
	v_cndmask_b32_e32 v1, v1, v4, vcc
	v_mul_lo_u32 v4, v2, v1
	v_add_u32_e32 v2, v4, v2
	v_cmp_ne_u32_e32 vcc, v3, v2
	s_and_saveexec_b64 s[4:5], vcc
	s_xor_b64 s[4:5], exec, s[4:5]
	s_cbranch_execz .LBB0_2914
	s_waitcnt lgkmcnt(0)
	s_add_u32 s12, s94, 0x1f803500
	s_addc_u32 s13, s95, 0
	v_mov_b32_e32 v0, 0
	s_nop 0
	global_load_dword v0, v0, s[12:13] sc1
	s_waitcnt vmcnt(0)
	v_cmp_eq_u32_e32 vcc, v0, v1
	s_and_saveexec_b64 s[6:7], vcc
	s_cbranch_execz .LBB0_2913
	s_add_u32 s8, s94, 0x1f800200
	s_addc_u32 s9, s95, 0
	s_mov_b32 s24, 1
	s_mov_b64 s[14:15], 0
	v_mov_b32_e32 v0, 0
	s_branch .LBB0_2904

; __device__ __forceinline__ unsigned xb_ld(unsigned* p)              { return __hip_atomic_load(p, __ATOMIC_RELAXED, __HIP_MEMORY_SCOPE_AGENT); }
; __device__ __forceinline__ unsigned xb_add(unsigned* p, unsigned v) { return __hip_atomic_fetch_add(p, v, __ATOMIC_RELAXED, __HIP_MEMORY_SCOPE_AGENT); }
; #define XB_SPIN(cond, bar) do { unsigned _sp = 0; while (cond) { __builtin_amdgcn_s_sleep(1); \
;     if ((++_sp & 255u) == 0u) { if (xb_ld(&(bar)[XB_TMO])) break; if (_sp > XB_SPIN_CAP) { atomicAdd(&(bar)[XB_TMO], 1u); break; } } } } while (0)
; __device__ __forceinline__ void xcd_barrier(const XcdBarrier& b) {
;     ...
;         const unsigned old = xb_add(&bar[XB_XSUB(b.x)], 1u);
;         const unsigned gen = old / nloc;
;         if (old + 1u == (gen + 1u) * nloc) {
;             __builtin_amdgcn_fence(__ATOMIC_RELEASE, "agent");
;             asm volatile("s_waitcnt vmcnt(0)" ::: "memory");
;             const unsigned og = xb_add(&bar[XB_TOP], 1u);
;             const unsigned tg = og / nx;
;             if (og + 1u == (tg + 1u) * nx) xb_add(&bar[XB_TOPGEN], 1u);
;             else XB_SPIN(xb_ld(&bar[XB_TOPGEN]) == tg, bar);
;             __builtin_amdgcn_fence(__ATOMIC_ACQUIRE, "agent");
;             xb_add(&bar[XB_XGEN(b.x)], 1u);
;             asm volatile("s_waitcnt vmcnt(0)" ::: "memory");
;         } else {
;             XB_SPIN(xb_ld(&bar[XB_XGEN(b.x)]) == gen, bar);
;             __builtin_amdgcn_fence(__ATOMIC_ACQUIRE, "agent");
;             asm volatile("s_waitcnt vmcnt(0)" ::: "memory");
;         }
.LBB0_3174:
	s_or_b64 exec, exec, s[6:7]
	v_cvt_f32_u32_e32 v4, v2
	s_waitcnt vmcnt(0)
	v_readfirstlane_b32 s4, v3
	v_sub_u32_e32 v3, 0, v2
	v_rcp_iflag_f32_e32 v4, v4
	v_add_u32_e32 v5, s4, v1
	v_mul_f32_e32 v4, 0x4f7ffffe, v4
	v_cvt_u32_f32_e32 v4, v4
	v_mul_lo_u32 v1, v3, v4
	v_mul_hi_u32 v1, v4, v1
	v_add_u32_e32 v1, v4, v1
	v_mul_hi_u32 v1, v5, v1
	v_mul_lo_u32 v3, v1, v2
	v_sub_u32_e32 v3, v5, v3
	v_add_u32_e32 v4, 1, v1
	v_cmp_ge_u32_e32 vcc, v3, v2
	s_nop 1
	v_cndmask_b32_e32 v1, v1, v4, vcc
	v_sub_u32_e32 v4, v3, v2
	v_cndmask_b32_e32 v3, v3, v4, vcc
	v_add_u32_e32 v4, 1, v1
	v_cmp_ge_u32_e32 vcc, v3, v2
	v_add_u32_e32 v3, 1, v5
	s_nop 0
	v_cndmask_b32_e32 v1, v1, v4, vcc
	v_mul_lo_u32 v4, v2, v1
	v_add_u32_e32 v2, v4, v2
	v_cmp_ne_u32_e32 vcc, v3, v2
	s_and_saveexec_b64 s[4:5], vcc
	s_xor_b64 s[4:5], exec, s[4:5]
	s_cbranch_execz .LBB0_3188
	s_waitcnt lgkmcnt(0)
	s_add_u32 s10, s94, 0x1f803500
	s_addc_u32 s11, s95, 0
	v_mov_b32_e32 v0, 0
	s_nop 0
	global_load_dword v0, v0, s[10:11] sc1
	s_waitcnt vmcnt(0)
	v_cmp_eq_u32_e32 vcc, v0, v1
	s_and_saveexec_b64 s[6:7], vcc
	s_cbranch_execz .LBB0_3187
	s_add_u32 s8, s94, 0x1f800200
	s_addc_u32 s9, s95, 0
	s_mov_b32 s22, 1
	s_mov_b64 s[12:13], 0
	v_mov_b32_e32 v0, 0
	s_branch .LBB0_3178
